# P5: D[head] load hoisted (no vmcnt(0) drains in head loop), B/C staging loads parallel; dattn 2 heads x 16 blocks per XCD; xattn dwordx4 stores
# speedup vs baseline: 1.0442x; 1.0020x over previous
.LBB0_1575:
	s_or_b64 exec, exec, s[92:93]
	v_readlane_b32 s4, v241, 46
	v_readlane_b32 s5, v241, 47
	v_mov_b32_e32 v133, v121
	v_readlane_b32 s40, v244, 15
	s_waitcnt lgkmcnt(1)
	v_cndmask_b32_e64 v2, 0, 1, s[4:5]
	v_readlane_b32 s4, v243, 14
	v_readfirstlane_b32 s91, v2
	s_lshl_b32 s92, s91, 3
	s_ashr_i32 s91, s90, 31
	s_lshl_b64 s[94:95], s[90:91], 10
	s_add_u32 s93, s4, s94
	v_readlane_b32 s4, v243, 15
	s_addc_u32 s95, s4, s95
	s_lshl_b32 s94, s96, 8
	s_add_u32 s94, s93, s94
	s_addc_u32 s95, s95, 0
	v_lshl_add_u64 v[4:5], s[94:95], 0, v[132:133]
	v_mov_b32_e32 v135, v121
	v_lshlrev_b32_e32 v0, 4, v2
	v_mov_b32_e32 v1, v121
	v_readlane_b32 s44, v244, 19
	v_readlane_b32 s45, v244, 20
	v_lshl_add_u64 v[6:7], v[4:5], 0, v[134:135]
	v_lshlrev_b32_e32 v76, 9, v2
	v_lshl_add_u64 v[146:147], s[44:45], 0, v[0:1]
	global_load_dwordx4 v[0:3], v[6:7], off
	v_mov_b32_e32 v137, v121
	v_add_u32_e32 v12, v175, v176
	v_lshl_add_u64 v[8:9], v[4:5], 0, v[136:137]
	v_mov_b32_e32 v139, v121
	v_add_u32_e32 v13, v175, v177
	v_lshl_add_u64 v[10:11], v[4:5], 0, v[138:139]
	v_mov_b32_e32 v141, v121
	v_lshl_add_u64 v[4:5], v[4:5], 0, v[140:141]
	global_load_dwordx4 v[16:19], v[8:9], off
	global_load_dwordx4 v[20:23], v[10:11], off
	global_load_dwordx4 v[24:27], v[4:5], off
	global_load_dwordx4 v[28:31], v[6:7], off offset:512
	global_load_dwordx4 v[32:35], v[8:9], off offset:512
	global_load_dwordx4 v[40:43], v[10:11], off offset:512
	global_load_dwordx4 v[44:47], v[4:5], off offset:512
	v_add_u32_e32 v14, v175, v178
	v_add_u32_e32 v48, v179, v183
	v_add_u32_e32 v36, v179, v184
	v_add_u32_e32 v52, v179, v185
	s_lshl_b32 s1, s1, 1
	s_lshl_b32 s0, s0, 4
	v_readlane_b32 s41, v244, 16
	s_lshl_b32 s10, s96, 9
	s_or_b32 s94, s0, s1
	s_mov_b32 s41, s11
	s_ashr_i32 s95, s94, 31
	s_lshl_b64 s[94:95], s[94:95], 14
	s_movk_i32 s1, 0x2000
	v_add_u32_e32 v54, s90, v187
	v_ashrrev_i32_e32 v55, 31, v54
	v_lshlrev_b64 v[74:75], 10, v[54:55]
	v_add_u32_e32 v78, s90, v204
	v_ashrrev_i32_e32 v79, 31, v78
	v_lshlrev_b64 v[80:81], 11, v[78:79]
	v_or3_b32 v80, v76, v128, v80
	v_mov_b32_e32 v156, 0
	v_mov_b32_e32 v133, v203
	v_mov_b32_e32 v135, v202
	v_mov_b32_e32 v137, v201
	v_mov_b32_e32 v139, v200
	v_mov_b32_e32 v141, v199
	v_mov_b32_e32 v143, v198
	v_mov_b32_e32 v215, v197
	v_mov_b32_e32 v216, v196
	v_mov_b32_e32 v217, v195
	v_mov_b32_e32 v218, v194
	v_mov_b32_e32 v157, v156
	v_mov_b32_e32 v158, v156
	v_mov_b32_e32 v159, v156
	v_readlane_b32 s42, v244, 17
	v_readlane_b32 s43, v244, 18
	v_readlane_b32 s46, v244, 21
	v_readlane_b32 s47, v244, 22
	v_readlane_b32 s48, v244, 23
	v_readlane_b32 s49, v244, 24
	v_readlane_b32 s50, v244, 25
	v_readlane_b32 s51, v244, 26
	v_readlane_b32 s52, v244, 27
	v_readlane_b32 s53, v244, 28
	v_readlane_b32 s54, v244, 29
	v_readlane_b32 s55, v244, 30
	s_waitcnt vmcnt(7)
	ds_write_b128 v12, v[0:3] offset:9216
	s_waitcnt vmcnt(6)
	ds_write_b128 v13, v[16:19] offset:9216
	s_waitcnt vmcnt(5)
	ds_write_b128 v12, v[20:23] offset:26624
	s_waitcnt vmcnt(4)
	ds_write_b128 v14, v[24:27] offset:9216
	s_waitcnt vmcnt(3)
	ds_write_b128 v12, v[28:31] offset:44032
	s_waitcnt vmcnt(2)
	ds_write_b128 v13, v[32:35] offset:44032
	s_waitcnt vmcnt(1)
	ds_write_b128 v12, v[40:43] offset:61440
	s_waitcnt vmcnt(0)
	ds_write_b128 v14, v[44:47] offset:44032
	s_waitcnt lgkmcnt(0)
	s_waitcnt lgkmcnt(0)
	s_barrier
	ds_read_b128 v[0:3], v145 offset:44032
	ds_read_b128 v[4:7], v145 offset:44096
	ds_read_b128 v[8:11], v145 offset:44160
	ds_read_b128 v[12:15], v145 offset:44224
	ds_read_b128 v[16:19], v48 offset:9216
	ds_read_b128 v[20:23], v48 offset:9280
	s_waitcnt lgkmcnt(1)
	v_mfma_f32_16x16x32_bf16 v[16:19], v[16:19], v[0:3], 0
	ds_read_b128 v[24:27], v48 offset:13632
	ds_read_b128 v[28:31], v48 offset:17984
	ds_read_b128 v[32:35], v36 offset:9280
	s_waitcnt lgkmcnt(3)
	v_mfma_f32_16x16x32_bf16 v[16:19], v[20:23], v[4:7], v[16:19]
	ds_read_b128 v[20:23], v48 offset:9344
	ds_read_b128 v[44:47], v48 offset:35392
	ds_read_b128 v[40:43], v48 offset:31040
	s_waitcnt lgkmcnt(2)
	v_mfma_f32_16x16x32_bf16 v[16:19], v[20:23], v[8:11], v[16:19]
	ds_read_b128 v[20:23], v48 offset:9408
	s_waitcnt lgkmcnt(0)
	v_mfma_f32_16x16x32_bf16 v[16:19], v[20:23], v[12:15], v[16:19]
	ds_read_b128 v[20:23], v48 offset:13568
	s_waitcnt lgkmcnt(0)
	v_mfma_f32_16x16x32_bf16 v[20:23], v[20:23], v[0:3], 0
	v_mfma_f32_16x16x32_bf16 v[20:23], v[24:27], v[4:7], v[20:23]
	ds_read_b128 v[24:27], v48 offset:13696
	s_waitcnt lgkmcnt(0)
	v_mfma_f32_16x16x32_bf16 v[20:23], v[24:27], v[8:11], v[20:23]
	ds_read_b128 v[24:27], v48 offset:13760
	s_waitcnt lgkmcnt(0)
	v_mfma_f32_16x16x32_bf16 v[20:23], v[24:27], v[12:15], v[20:23]
	ds_read_b128 v[24:27], v48 offset:17920
	s_waitcnt lgkmcnt(0)
	v_mfma_f32_16x16x32_bf16 v[24:27], v[24:27], v[0:3], 0
	v_mfma_f32_16x16x32_bf16 v[24:27], v[28:31], v[4:7], v[24:27]
	ds_read_b128 v[28:31], v48 offset:18048
	s_waitcnt lgkmcnt(0)
	v_mfma_f32_16x16x32_bf16 v[24:27], v[28:31], v[8:11], v[24:27]
	ds_read_b128 v[28:31], v48 offset:18112
	s_waitcnt lgkmcnt(0)
	v_mfma_f32_16x16x32_bf16 v[24:27], v[28:31], v[12:15], v[24:27]
	ds_read_b128 v[28:31], v36 offset:9216
	s_waitcnt lgkmcnt(0)
	v_mfma_f32_16x16x32_bf16 v[28:31], v[28:31], v[0:3], 0
	v_mfma_f32_16x16x32_bf16 v[28:31], v[32:35], v[4:7], v[28:31]
	ds_read_b128 v[32:35], v36 offset:9344
	s_waitcnt lgkmcnt(0)
	v_mfma_f32_16x16x32_bf16 v[28:31], v[32:35], v[8:11], v[28:31]
	ds_read_b128 v[32:35], v36 offset:9408
	ds_read_b128 v[36:39], v48 offset:26688
	s_waitcnt lgkmcnt(1)
	v_mfma_f32_16x16x32_bf16 v[28:31], v[32:35], v[12:15], v[28:31]
	ds_read_b128 v[32:35], v48 offset:26624
	s_waitcnt lgkmcnt(0)
	v_mfma_f32_16x16x32_bf16 v[32:35], v[32:35], v[0:3], 0
	v_mfma_f32_16x16x32_bf16 v[32:35], v[36:39], v[4:7], v[32:35]
	ds_read_b128 v[36:39], v48 offset:26752
	s_waitcnt lgkmcnt(0)
	v_mfma_f32_16x16x32_bf16 v[32:35], v[36:39], v[8:11], v[32:35]
	ds_read_b128 v[36:39], v48 offset:26816
	s_waitcnt lgkmcnt(0)
	v_mfma_f32_16x16x32_bf16 v[32:35], v[36:39], v[12:15], v[32:35]
	ds_read_b128 v[36:39], v48 offset:30976
	s_waitcnt lgkmcnt(0)
	v_mfma_f32_16x16x32_bf16 v[36:39], v[36:39], v[0:3], 0
	v_mfma_f32_16x16x32_bf16 v[36:39], v[40:43], v[4:7], v[36:39]
	ds_read_b128 v[40:43], v48 offset:31104
	s_waitcnt lgkmcnt(0)
	v_mfma_f32_16x16x32_bf16 v[36:39], v[40:43], v[8:11], v[36:39]
	ds_read_b128 v[40:43], v48 offset:31168
	s_waitcnt lgkmcnt(0)
	v_mfma_f32_16x16x32_bf16 v[36:39], v[40:43], v[12:15], v[36:39]
	ds_read_b128 v[40:43], v48 offset:35328
	s_waitcnt lgkmcnt(0)
	v_mfma_f32_16x16x32_bf16 v[40:43], v[40:43], v[0:3], 0
	v_mfma_f32_16x16x32_bf16 v[40:43], v[44:47], v[4:7], v[40:43]
	ds_read_b128 v[44:47], v48 offset:35456
	s_waitcnt lgkmcnt(0)
	v_mfma_f32_16x16x32_bf16 v[40:43], v[44:47], v[8:11], v[40:43]
	ds_read_b128 v[44:47], v48 offset:35520
	ds_read_b128 v[48:51], v52 offset:9280
	s_waitcnt lgkmcnt(1)
	v_mfma_f32_16x16x32_bf16 v[40:43], v[44:47], v[12:15], v[40:43]
	ds_read_b128 v[44:47], v52 offset:9216
	s_waitcnt lgkmcnt(0)
	v_mfma_f32_16x16x32_bf16 v[44:47], v[44:47], v[0:3], 0
	v_mfma_f32_16x16x32_bf16 v[44:47], v[48:51], v[4:7], v[44:47]
	ds_read_b128 v[48:51], v52 offset:9344
	s_waitcnt lgkmcnt(0)
	v_mfma_f32_16x16x32_bf16 v[44:47], v[48:51], v[8:11], v[44:47]
	ds_read_b128 v[48:51], v52 offset:9408
	v_lshl_add_u64 v[52:53], v[122:123], 0, s[10:11]
	v_readlane_b32 s4, v244, 0
	v_readlane_b32 s8, v244, 4
	v_readlane_b32 s9, v244, 5
	s_add_u32 s94, s8, s94
	s_addc_u32 s95, s9, s95
	v_lshl_add_u64 v[68:69], s[94:95], 0, v[120:121]
	s_waitcnt lgkmcnt(0)
	v_mfma_f32_16x16x32_bf16 v[44:47], v[48:51], v[12:15], v[44:47]
	v_or_b32_e32 v48, s90, v186
	v_add_co_u32_e32 v60, vcc, s1, v68
	v_ashrrev_i32_e32 v49, 31, v48
	s_nop 0
	v_addc_co_u32_e32 v61, vcc, 0, v69, vcc
	s_movk_i32 s1, 0x6000
	v_lshlrev_b64 v[72:73], 10, v[48:49]
	v_add_co_u32_e32 v68, vcc, s1, v68
	v_lshl_add_u64 v[48:49], v[52:53], 0, v[72:73]
	v_lshl_add_u64 v[52:53], v[52:53], 0, v[74:75]
	v_addc_co_u32_e32 v69, vcc, 0, v69, vcc
	global_load_dwordx4 v[48:51], v[48:49], off
	v_or_b32_e32 v72, v72, v76
	global_load_dwordx4 v[52:55], v[52:53], off
	v_lshl_add_u64 v[152:153], v[126:127], 0, v[72:73]
	global_load_dwordx4 v[56:59], v120, s[94:95]
	s_nop 0
	global_load_dwordx4 v[60:63], v[60:61], off
	s_nop 0
	global_load_dwordx4 v[64:67], v205, s[94:95]
	v_lshlrev_b64 v[72:73], 10, v[78:79]
	global_load_dwordx4 v[68:71], v[68:69], off
	v_readlane_b32 s10, v244, 6
	v_readlane_b32 s11, v244, 7
	s_or_b32 s0, s0, s92
	v_or_b32_e32 v74, v74, v76
	v_or_b32_e32 v72, v72, v76
	s_or_b32 s92, s0, 2
	v_lshl_add_u64 v[148:149], s[10:11], 0, v[80:81]
	v_lshl_add_u64 v[150:151], v[126:127], 0, v[74:75]
	v_lshl_add_u64 v[154:155], v[130:131], 0, v[72:73]
	s_movk_i32 s0, 0x2004
	s_mov_b64 s[94:95], 0
	v_readlane_b32 s5, v244, 1
	v_readlane_b32 s6, v244, 2
	v_readlane_b32 s7, v244, 3
	s_branch .LBB0_1577
